# squared-relu GEMM epilogues: redundant v_max x,x,x canonicalisations before fmaxf(x,0) removed (wide-store WAR wait states re-derived)
# baseline (speedup 1.0000x reference)
.LBB0_441:
	v_lshl_add_u32 v152, s30, 8, v146
	v_ashrrev_i32_e32 v153, 31, v152
	v_max_f32_e32 v120, 0, v120
	v_lshl_add_u32 v144, s75, 8, v148
	v_lshlrev_b64 v[154:155], 13, v[152:153]
	v_mul_f32_e32 v153, v120, v120
	v_max_f32_e32 v121, 0, v121
	v_max_f32_e32 v122, 0, v122
	v_ashrrev_i32_e32 v145, 31, v144
	v_max_f32_e32 v120, 0, v125
	v_mul_f32_e32 v125, v121, v121
	v_max_f32_e32 v121, v126, v126
	v_mul_f32_e32 v126, v122, v122
	v_lshl_add_u64 v[154:155], s[44:45], 0, v[154:155]
	v_lshlrev_b64 v[156:157], 1, v[144:145]
	v_max_f32_e32 v124, 0, v124
	v_mul_f32_e32 v120, v120, v120
	v_max_f32_e32 v121, 0, v121
	v_max_f32_e32 v122, 0, v127
	v_max_f32_e32 v123, 0, v123
	v_lshl_add_u64 v[144:145], v[154:155], 0, v[156:157]
	v_mul_f32_e32 v124, v124, v124
	v_mul_f32_e32 v121, v121, v121
	v_mul_f32_e32 v122, v122, v122
	v_mul_f32_e32 v123, v123, v123
	v_cvt_pk_bf16_f32 v120, v124, v120
	v_max_f32_e32 v112, 0, v112
	v_cvt_pk_bf16_f32 v121, v121, v122
	v_cvt_pk_bf16_f32 v122, v153, v125
	v_cvt_pk_bf16_f32 v123, v126, v123
	global_store_dwordx4 v[144:145], v[120:123], off
	v_max_f32_e32 v113, 0, v113
	v_max_f32_e32 v114, 0, v114
	v_mul_f32_e32 v120, v112, v112
	v_max_f32_e32 v112, 0, v117
	v_mul_f32_e32 v117, v113, v113
	v_max_f32_e32 v113, v118, v118
	v_mul_f32_e32 v118, v114, v114
	v_max_f32_e32 v116, 0, v116
	v_mul_f32_e32 v112, v112, v112
	v_max_f32_e32 v113, 0, v113
	v_max_f32_e32 v114, 0, v119
	v_max_f32_e32 v115, 0, v115
	v_mul_f32_e32 v116, v116, v116
	v_mul_f32_e32 v113, v113, v113
	v_mul_f32_e32 v114, v114, v114
	v_mul_f32_e32 v115, v115, v115
	v_cvt_pk_bf16_f32 v112, v116, v112
	v_cvt_pk_bf16_f32 v113, v113, v114
	v_cvt_pk_bf16_f32 v114, v120, v117
	v_cvt_pk_bf16_f32 v115, v118, v115
	global_store_dwordx4 v[144:145], v[112:115], off offset:256
	v_max_f32_e32 v104, 0, v104
	s_nop 0
	v_or_b32_e32 v112, 16, v152
	v_ashrrev_i32_e32 v113, 31, v112
	v_mul_f32_e32 v114, v104, v104
	v_max_f32_e32 v105, 0, v105
	v_max_f32_e32 v106, 0, v106
	v_lshlrev_b64 v[112:113], 13, v[112:113]
	v_max_f32_e32 v104, 0, v109
	v_mul_f32_e32 v109, v105, v105
	v_max_f32_e32 v105, v110, v110
	v_mul_f32_e32 v110, v106, v106
	v_lshl_add_u64 v[112:113], s[44:45], 0, v[112:113]
	v_max_f32_e32 v108, 0, v108
	v_mul_f32_e32 v104, v104, v104
	v_max_f32_e32 v105, 0, v105
	v_max_f32_e32 v106, 0, v111
	v_max_f32_e32 v107, 0, v107
	v_lshl_add_u64 v[112:113], v[112:113], 0, v[156:157]
	v_mul_f32_e32 v108, v108, v108
	v_mul_f32_e32 v105, v105, v105
	v_mul_f32_e32 v106, v106, v106
	v_mul_f32_e32 v107, v107, v107
	v_cvt_pk_bf16_f32 v104, v108, v104
	v_max_f32_e32 v96, 0, v96
	v_cvt_pk_bf16_f32 v105, v105, v106
	v_cvt_pk_bf16_f32 v106, v114, v109
	v_cvt_pk_bf16_f32 v107, v110, v107
	global_store_dwordx4 v[112:113], v[104:107], off
	v_max_f32_e32 v97, 0, v97
	v_max_f32_e32 v98, 0, v98
	v_mul_f32_e32 v104, v96, v96
	v_max_f32_e32 v96, 0, v101
	v_mul_f32_e32 v101, v97, v97
	v_max_f32_e32 v97, v102, v102
	v_mul_f32_e32 v102, v98, v98
	v_max_f32_e32 v100, 0, v100
	v_mul_f32_e32 v96, v96, v96
	v_max_f32_e32 v97, 0, v97
	v_max_f32_e32 v98, 0, v103
	v_max_f32_e32 v99, 0, v99
	v_mul_f32_e32 v100, v100, v100
	v_mul_f32_e32 v97, v97, v97
	v_mul_f32_e32 v98, v98, v98
	v_mul_f32_e32 v99, v99, v99
	v_cvt_pk_bf16_f32 v96, v100, v96
	v_cvt_pk_bf16_f32 v97, v97, v98
	v_cvt_pk_bf16_f32 v98, v104, v101
	v_cvt_pk_bf16_f32 v99, v102, v99
	global_store_dwordx4 v[112:113], v[96:99], off offset:256
	v_max_f32_e32 v88, 0, v88
	s_nop 0
	v_or_b32_e32 v96, 32, v152
	v_ashrrev_i32_e32 v97, 31, v96
	v_mul_f32_e32 v98, v88, v88
	v_max_f32_e32 v89, 0, v89
	v_max_f32_e32 v90, 0, v90
	v_lshlrev_b64 v[96:97], 13, v[96:97]
	v_max_f32_e32 v88, 0, v93
	v_mul_f32_e32 v93, v89, v89
	v_max_f32_e32 v89, v94, v94
	v_mul_f32_e32 v94, v90, v90
	v_lshl_add_u64 v[96:97], s[44:45], 0, v[96:97]
	v_max_f32_e32 v92, 0, v92
	v_mul_f32_e32 v88, v88, v88
	v_max_f32_e32 v89, 0, v89
	v_max_f32_e32 v90, 0, v95
	v_max_f32_e32 v91, 0, v91
	v_lshl_add_u64 v[96:97], v[96:97], 0, v[156:157]
	v_mul_f32_e32 v92, v92, v92
	v_mul_f32_e32 v89, v89, v89
	v_mul_f32_e32 v90, v90, v90
	v_mul_f32_e32 v91, v91, v91
	v_cvt_pk_bf16_f32 v88, v92, v88
	v_max_f32_e32 v80, 0, v80
	v_cvt_pk_bf16_f32 v89, v89, v90
	v_cvt_pk_bf16_f32 v90, v98, v93
	v_cvt_pk_bf16_f32 v91, v94, v91
	global_store_dwordx4 v[96:97], v[88:91], off
	v_max_f32_e32 v81, 0, v81
	v_max_f32_e32 v82, 0, v82
	v_mul_f32_e32 v88, v80, v80
	v_max_f32_e32 v80, 0, v85
	v_mul_f32_e32 v85, v81, v81
	v_max_f32_e32 v81, v86, v86
	v_mul_f32_e32 v86, v82, v82
	v_max_f32_e32 v84, 0, v84
	v_mul_f32_e32 v80, v80, v80
	v_max_f32_e32 v81, 0, v81
	v_max_f32_e32 v82, 0, v87
	v_max_f32_e32 v83, 0, v83
	v_mul_f32_e32 v84, v84, v84
	v_mul_f32_e32 v81, v81, v81
	v_mul_f32_e32 v82, v82, v82
	v_mul_f32_e32 v83, v83, v83
	v_cvt_pk_bf16_f32 v80, v84, v80
	v_cvt_pk_bf16_f32 v81, v81, v82
	v_cvt_pk_bf16_f32 v82, v88, v85
	v_cvt_pk_bf16_f32 v83, v86, v83
	global_store_dwordx4 v[96:97], v[80:83], off offset:256
	v_max_f32_e32 v72, 0, v72
	s_nop 0
	v_or_b32_e32 v80, 48, v152
	v_ashrrev_i32_e32 v81, 31, v80
	v_mul_f32_e32 v82, v72, v72
	v_max_f32_e32 v73, 0, v73
	v_max_f32_e32 v74, 0, v74
	v_lshlrev_b64 v[80:81], 13, v[80:81]
	v_max_f32_e32 v72, 0, v77
	v_mul_f32_e32 v77, v73, v73
	v_max_f32_e32 v73, v78, v78
	v_mul_f32_e32 v78, v74, v74
	v_lshl_add_u64 v[80:81], s[44:45], 0, v[80:81]
	v_max_f32_e32 v76, 0, v76
	v_mul_f32_e32 v72, v72, v72
	v_max_f32_e32 v73, 0, v73
	v_max_f32_e32 v74, 0, v79
	v_max_f32_e32 v75, 0, v75
	v_lshl_add_u64 v[80:81], v[80:81], 0, v[156:157]
	v_mul_f32_e32 v76, v76, v76
	v_mul_f32_e32 v73, v73, v73
	v_mul_f32_e32 v74, v74, v74
	v_mul_f32_e32 v75, v75, v75
	v_cvt_pk_bf16_f32 v72, v76, v72
	v_max_f32_e32 v64, 0, v64
	v_max_f32_e32 v65, 0, v65
	v_max_f32_e32 v66, 0, v66
	v_cvt_pk_bf16_f32 v73, v73, v74
	v_cvt_pk_bf16_f32 v74, v82, v77
	v_cvt_pk_bf16_f32 v75, v78, v75
	global_store_dwordx4 v[80:81], v[72:75], off
	s_nop 1
	v_mul_f32_e32 v72, v64, v64
	v_max_f32_e32 v64, v69, v69
	v_mul_f32_e32 v69, v65, v65
	v_max_f32_e32 v65, v70, v70
	v_mul_f32_e32 v70, v66, v66
	v_max_f32_e32 v64, 0, v64
	v_max_f32_e32 v65, 0, v65
	v_max_f32_e32 v66, 0, v71
	v_max_f32_e32 v68, 0, v68
	v_mul_f32_e32 v64, v64, v64
	v_mul_f32_e32 v65, v65, v65
	v_max_f32_e32 v67, 0, v67
	v_mul_f32_e32 v66, v66, v66
	v_mul_f32_e32 v68, v68, v68
	v_mul_f32_e32 v67, v67, v67
	v_cvt_pk_bf16_f32 v64, v68, v64
	v_cvt_pk_bf16_f32 v65, v65, v66
	v_cvt_pk_bf16_f32 v66, v72, v69
	v_max_f32_e32 v56, 0, v56
	v_cvt_pk_bf16_f32 v67, v70, v67
	global_store_dwordx4 v[80:81], v[64:67], off offset:256
	v_max_f32_e32 v57, 0, v57
	s_nop 0
	v_mul_f32_e32 v66, v56, v56
	v_max_f32_e32 v58, 0, v58
	v_max_f32_e32 v60, 0, v60
	v_max_f32_e32 v56, 0, v61
	v_mul_f32_e32 v61, v57, v57
	v_max_f32_e32 v57, v62, v62
	v_mul_f32_e32 v62, v58, v58
	v_mul_f32_e32 v60, v60, v60
	v_mul_f32_e32 v56, v56, v56
	v_max_f32_e32 v57, 0, v57
	v_max_f32_e32 v58, 0, v63
	v_mul_f32_e32 v57, v57, v57
	v_max_f32_e32 v59, 0, v59
	v_mul_f32_e32 v58, v58, v58
	v_cvt_pk_bf16_f32 v56, v60, v56
	v_add_co_u32_e32 v60, vcc, s71, v144
	v_mul_f32_e32 v59, v59, v59
	v_cvt_pk_bf16_f32 v57, v57, v58
	v_cvt_pk_bf16_f32 v58, v66, v61
	v_addc_co_u32_e32 v61, vcc, 0, v145, vcc
	v_max_f32_e32 v48, 0, v48
	v_max_f32_e32 v49, 0, v49
	v_max_f32_e32 v50, 0, v50
	v_cvt_pk_bf16_f32 v59, v62, v59
	global_store_dwordx4 v[60:61], v[56:59], off
	s_nop 1
	v_mul_f32_e32 v56, v48, v48
	v_max_f32_e32 v48, v53, v53
	v_mul_f32_e32 v53, v49, v49
	v_max_f32_e32 v49, v54, v54
	v_mul_f32_e32 v54, v50, v50
	v_max_f32_e32 v48, 0, v48
	v_max_f32_e32 v49, 0, v49
	v_max_f32_e32 v50, 0, v55
	v_max_f32_e32 v52, 0, v52
	v_mul_f32_e32 v48, v48, v48
	v_mul_f32_e32 v49, v49, v49
	v_max_f32_e32 v51, 0, v51
	v_mul_f32_e32 v50, v50, v50
	v_lshl_add_u64 v[64:65], v[144:145], 0, s[12:13]
	v_mul_f32_e32 v52, v52, v52
	v_mul_f32_e32 v51, v51, v51
	v_cvt_pk_bf16_f32 v48, v52, v48
	v_cvt_pk_bf16_f32 v49, v49, v50
	v_cvt_pk_bf16_f32 v50, v56, v53
	v_max_f32_e32 v40, 0, v40
	v_cvt_pk_bf16_f32 v51, v54, v51
	global_store_dwordx4 v[64:65], v[48:51], off offset:256
	v_max_f32_e32 v41, 0, v41
	s_nop 0
	v_mul_f32_e32 v50, v40, v40
	v_max_f32_e32 v42, 0, v42
	v_max_f32_e32 v44, 0, v44
	v_max_f32_e32 v40, 0, v45
	v_mul_f32_e32 v45, v41, v41
	v_max_f32_e32 v41, v46, v46
	v_mul_f32_e32 v46, v42, v42
	v_mul_f32_e32 v44, v44, v44
	v_mul_f32_e32 v40, v40, v40
	v_max_f32_e32 v41, 0, v41
	v_max_f32_e32 v42, 0, v47
	v_mul_f32_e32 v41, v41, v41
	v_max_f32_e32 v43, 0, v43
	v_mul_f32_e32 v42, v42, v42
	v_cvt_pk_bf16_f32 v40, v44, v40
	v_add_co_u32_e32 v44, vcc, s72, v144
	v_mul_f32_e32 v43, v43, v43
	v_cvt_pk_bf16_f32 v41, v41, v42
	v_cvt_pk_bf16_f32 v42, v50, v45
	v_addc_co_u32_e32 v45, vcc, 0, v145, vcc
	v_max_f32_e32 v32, 0, v32
	v_max_f32_e32 v33, 0, v33
	v_max_f32_e32 v34, 0, v34
	v_cvt_pk_bf16_f32 v43, v46, v43
	global_store_dwordx4 v[44:45], v[40:43], off
	s_nop 1
	v_mul_f32_e32 v40, v32, v32
	v_max_f32_e32 v32, v37, v37
	v_mul_f32_e32 v37, v33, v33
	v_max_f32_e32 v33, v38, v38
	v_mul_f32_e32 v38, v34, v34
	v_max_f32_e32 v32, 0, v32
	v_max_f32_e32 v33, 0, v33
	v_max_f32_e32 v34, 0, v39
	v_max_f32_e32 v36, 0, v36
	v_mul_f32_e32 v32, v32, v32
	v_mul_f32_e32 v33, v33, v33
	v_max_f32_e32 v35, 0, v35
	v_mul_f32_e32 v34, v34, v34
	v_lshl_add_u64 v[48:49], v[144:145], 0, s[14:15]
	v_mul_f32_e32 v36, v36, v36
	v_mul_f32_e32 v35, v35, v35
	v_cvt_pk_bf16_f32 v32, v36, v32
	v_cvt_pk_bf16_f32 v33, v33, v34
	v_cvt_pk_bf16_f32 v34, v40, v37
	v_max_f32_e32 v24, 0, v24
	v_cvt_pk_bf16_f32 v35, v38, v35
	global_store_dwordx4 v[48:49], v[32:35], off offset:256
	v_max_f32_e32 v25, 0, v25
	s_nop 0
	v_mul_f32_e32 v34, v24, v24
	v_max_f32_e32 v26, 0, v26
	v_max_f32_e32 v28, 0, v28
	v_max_f32_e32 v24, 0, v29
	v_mul_f32_e32 v29, v25, v25
	v_max_f32_e32 v25, v30, v30
	v_mul_f32_e32 v30, v26, v26
	v_mul_f32_e32 v28, v28, v28
	v_mul_f32_e32 v24, v24, v24
	v_max_f32_e32 v25, 0, v25
	v_max_f32_e32 v26, 0, v31
	v_mul_f32_e32 v25, v25, v25
	v_max_f32_e32 v27, 0, v27
	v_mul_f32_e32 v26, v26, v26
	v_cvt_pk_bf16_f32 v24, v28, v24
	v_add_co_u32_e32 v28, vcc, s73, v144
	v_mul_f32_e32 v27, v27, v27
	v_cvt_pk_bf16_f32 v25, v25, v26
	v_cvt_pk_bf16_f32 v26, v34, v29
	v_addc_co_u32_e32 v29, vcc, 0, v145, vcc
	v_max_f32_e32 v16, 0, v16
	v_max_f32_e32 v17, 0, v17
	v_max_f32_e32 v18, 0, v18
	v_cvt_pk_bf16_f32 v27, v30, v27
	global_store_dwordx4 v[28:29], v[24:27], off
	s_nop 1
	v_mul_f32_e32 v24, v16, v16
	v_max_f32_e32 v16, v21, v21
	v_mul_f32_e32 v21, v17, v17
	v_max_f32_e32 v17, v22, v22
	v_mul_f32_e32 v22, v18, v18
	v_max_f32_e32 v16, 0, v16
	v_max_f32_e32 v17, 0, v17
	v_max_f32_e32 v18, 0, v23
	v_max_f32_e32 v20, 0, v20
	v_mul_f32_e32 v16, v16, v16
	v_mul_f32_e32 v17, v17, v17
	v_max_f32_e32 v19, 0, v19
	v_mul_f32_e32 v18, v18, v18
	v_lshl_add_u64 v[32:33], v[144:145], 0, s[16:17]
	v_mul_f32_e32 v20, v20, v20
	v_mul_f32_e32 v19, v19, v19
	v_cvt_pk_bf16_f32 v16, v20, v16
	v_cvt_pk_bf16_f32 v17, v17, v18
	v_cvt_pk_bf16_f32 v18, v24, v21
	v_max_f32_e32 v8, 0, v8
	v_cvt_pk_bf16_f32 v19, v22, v19
	global_store_dwordx4 v[32:33], v[16:19], off offset:256
	v_max_f32_e32 v9, 0, v9
	s_nop 0
	v_mul_f32_e32 v18, v8, v8
	v_max_f32_e32 v10, 0, v10
	v_max_f32_e32 v12, 0, v12
	v_max_f32_e32 v8, 0, v13
	v_mul_f32_e32 v13, v9, v9
	v_max_f32_e32 v9, v14, v14
	v_mul_f32_e32 v14, v10, v10
	v_mul_f32_e32 v12, v12, v12
	v_mul_f32_e32 v8, v8, v8
	v_max_f32_e32 v9, 0, v9
	v_max_f32_e32 v10, 0, v15
	v_mul_f32_e32 v9, v9, v9
	v_max_f32_e32 v11, 0, v11
	v_mul_f32_e32 v10, v10, v10
	v_cvt_pk_bf16_f32 v8, v12, v8
	v_add_co_u32_e32 v12, vcc, s74, v144
	v_mul_f32_e32 v11, v11, v11
	v_cvt_pk_bf16_f32 v9, v9, v10
	v_cvt_pk_bf16_f32 v10, v18, v13
	v_addc_co_u32_e32 v13, vcc, 0, v145, vcc
	v_max_f32_e32 v0, 0, v0
	v_max_f32_e32 v1, 0, v1
	v_max_f32_e32 v2, 0, v2
	v_cvt_pk_bf16_f32 v11, v14, v11
	global_store_dwordx4 v[12:13], v[8:11], off
	s_nop 1
	v_mul_f32_e32 v8, v0, v0
	v_max_f32_e32 v0, v5, v5
	v_mul_f32_e32 v5, v1, v1
	v_max_f32_e32 v1, v6, v6
	v_mul_f32_e32 v6, v2, v2
	v_max_f32_e32 v0, 0, v0
	v_max_f32_e32 v1, 0, v1
	v_max_f32_e32 v2, 0, v7
	v_max_f32_e32 v3, 0, v3
	v_lshl_add_u64 v[16:17], v[144:145], 0, s[18:19]
	v_max_f32_e32 v4, 0, v4
	v_mul_f32_e32 v0, v0, v0
	v_mul_f32_e32 v1, v1, v1
	v_mul_f32_e32 v2, v2, v2
	v_mul_f32_e32 v3, v3, v3
	s_andn2_b64 vcc, exec, s[4:5]
	s_mov_b64 s[4:5], -1
	v_mul_f32_e32 v4, v4, v4
	v_cvt_pk_bf16_f32 v0, v4, v0
	v_cvt_pk_bf16_f32 v1, v1, v2
	v_cvt_pk_bf16_f32 v2, v8, v5
	v_cvt_pk_bf16_f32 v3, v6, v3
	global_store_dwordx4 v[16:17], v[0:3], off offset:256
	s_cbranch_vccnz .LBB0_434
	s_andn2_b64 vcc, exec, s[6:7]
	s_cbranch_vccnz .LBB0_433
	s_barrier
	s_branch .LBB0_433

.LBB0_1885:
	v_lshl_add_u32 v152, s36, 8, v146
	v_ashrrev_i32_e32 v153, 31, v152
	v_max_f32_e32 v120, 0, v120
	v_lshl_add_u32 v144, s71, 8, v148
	v_lshlrev_b64 v[154:155], 13, v[152:153]
	v_mul_f32_e32 v153, v120, v120
	v_max_f32_e32 v121, 0, v121
	v_max_f32_e32 v122, 0, v122
	v_ashrrev_i32_e32 v145, 31, v144
	v_max_f32_e32 v120, 0, v125
	v_mul_f32_e32 v125, v121, v121
	v_max_f32_e32 v121, v126, v126
	v_mul_f32_e32 v126, v122, v122
	v_lshl_add_u64 v[154:155], s[44:45], 0, v[154:155]
	v_lshlrev_b64 v[156:157], 1, v[144:145]
	v_max_f32_e32 v124, 0, v124
	v_mul_f32_e32 v120, v120, v120
	v_max_f32_e32 v121, 0, v121
	v_max_f32_e32 v122, 0, v127
	v_max_f32_e32 v123, 0, v123
	v_lshl_add_u64 v[144:145], v[154:155], 0, v[156:157]
	v_mul_f32_e32 v124, v124, v124
	v_mul_f32_e32 v121, v121, v121
	v_mul_f32_e32 v122, v122, v122
	v_mul_f32_e32 v123, v123, v123
	v_cvt_pk_bf16_f32 v120, v124, v120
	v_max_f32_e32 v112, 0, v112
	v_cvt_pk_bf16_f32 v121, v121, v122
	v_cvt_pk_bf16_f32 v122, v153, v125
	v_cvt_pk_bf16_f32 v123, v126, v123
	global_store_dwordx4 v[144:145], v[120:123], off
	v_max_f32_e32 v113, 0, v113
	v_max_f32_e32 v114, 0, v114
	v_mul_f32_e32 v120, v112, v112
	v_max_f32_e32 v112, 0, v117
	v_mul_f32_e32 v117, v113, v113
	v_max_f32_e32 v113, v118, v118
	v_mul_f32_e32 v118, v114, v114
	v_max_f32_e32 v116, 0, v116
	v_mul_f32_e32 v112, v112, v112
	v_max_f32_e32 v113, 0, v113
	v_max_f32_e32 v114, 0, v119
	v_max_f32_e32 v115, 0, v115
	v_mul_f32_e32 v116, v116, v116
	v_mul_f32_e32 v113, v113, v113
	v_mul_f32_e32 v114, v114, v114
	v_mul_f32_e32 v115, v115, v115
	v_cvt_pk_bf16_f32 v112, v116, v112
	v_cvt_pk_bf16_f32 v113, v113, v114
	v_cvt_pk_bf16_f32 v114, v120, v117
	v_cvt_pk_bf16_f32 v115, v118, v115
	global_store_dwordx4 v[144:145], v[112:115], off offset:256
	v_max_f32_e32 v104, 0, v104
	s_nop 0
	v_or_b32_e32 v112, 16, v152
	v_ashrrev_i32_e32 v113, 31, v112
	v_mul_f32_e32 v114, v104, v104
	v_max_f32_e32 v105, 0, v105
	v_max_f32_e32 v106, 0, v106
	v_lshlrev_b64 v[112:113], 13, v[112:113]
	v_max_f32_e32 v104, 0, v109
	v_mul_f32_e32 v109, v105, v105
	v_max_f32_e32 v105, v110, v110
	v_mul_f32_e32 v110, v106, v106
	v_lshl_add_u64 v[112:113], s[44:45], 0, v[112:113]
	v_max_f32_e32 v108, 0, v108
	v_mul_f32_e32 v104, v104, v104
	v_max_f32_e32 v105, 0, v105
	v_max_f32_e32 v106, 0, v111
	v_max_f32_e32 v107, 0, v107
	v_lshl_add_u64 v[112:113], v[112:113], 0, v[156:157]
	v_mul_f32_e32 v108, v108, v108
	v_mul_f32_e32 v105, v105, v105
	v_mul_f32_e32 v106, v106, v106
	v_mul_f32_e32 v107, v107, v107
	v_cvt_pk_bf16_f32 v104, v108, v104
	v_max_f32_e32 v96, 0, v96
	v_cvt_pk_bf16_f32 v105, v105, v106
	v_cvt_pk_bf16_f32 v106, v114, v109
	v_cvt_pk_bf16_f32 v107, v110, v107
	global_store_dwordx4 v[112:113], v[104:107], off
	v_max_f32_e32 v97, 0, v97
	v_max_f32_e32 v98, 0, v98
	v_mul_f32_e32 v104, v96, v96
	v_max_f32_e32 v96, 0, v101
	v_mul_f32_e32 v101, v97, v97
	v_max_f32_e32 v97, v102, v102
	v_mul_f32_e32 v102, v98, v98
	v_max_f32_e32 v100, 0, v100
	v_mul_f32_e32 v96, v96, v96
	v_max_f32_e32 v97, 0, v97
	v_max_f32_e32 v98, 0, v103
	v_max_f32_e32 v99, 0, v99
	v_mul_f32_e32 v100, v100, v100
	v_mul_f32_e32 v97, v97, v97
	v_mul_f32_e32 v98, v98, v98
	v_mul_f32_e32 v99, v99, v99
	v_cvt_pk_bf16_f32 v96, v100, v96
	v_cvt_pk_bf16_f32 v97, v97, v98
	v_cvt_pk_bf16_f32 v98, v104, v101
	v_cvt_pk_bf16_f32 v99, v102, v99
	global_store_dwordx4 v[112:113], v[96:99], off offset:256
	v_max_f32_e32 v88, 0, v88
	s_nop 0
	v_or_b32_e32 v96, 32, v152
	v_ashrrev_i32_e32 v97, 31, v96
	v_mul_f32_e32 v98, v88, v88
	v_max_f32_e32 v89, 0, v89
	v_max_f32_e32 v90, 0, v90
	v_lshlrev_b64 v[96:97], 13, v[96:97]
	v_max_f32_e32 v88, 0, v93
	v_mul_f32_e32 v93, v89, v89
	v_max_f32_e32 v89, v94, v94
	v_mul_f32_e32 v94, v90, v90
	v_lshl_add_u64 v[96:97], s[44:45], 0, v[96:97]
	v_max_f32_e32 v92, 0, v92
	v_mul_f32_e32 v88, v88, v88
	v_max_f32_e32 v89, 0, v89
	v_max_f32_e32 v90, 0, v95
	v_max_f32_e32 v91, 0, v91
	v_lshl_add_u64 v[96:97], v[96:97], 0, v[156:157]
	v_mul_f32_e32 v92, v92, v92
	v_mul_f32_e32 v89, v89, v89
	v_mul_f32_e32 v90, v90, v90
	v_mul_f32_e32 v91, v91, v91
	v_cvt_pk_bf16_f32 v88, v92, v88
	v_max_f32_e32 v80, 0, v80
	v_cvt_pk_bf16_f32 v89, v89, v90
	v_cvt_pk_bf16_f32 v90, v98, v93
	v_cvt_pk_bf16_f32 v91, v94, v91
	global_store_dwordx4 v[96:97], v[88:91], off
	v_max_f32_e32 v81, 0, v81
	v_max_f32_e32 v82, 0, v82
	v_mul_f32_e32 v88, v80, v80
	v_max_f32_e32 v80, 0, v85
	v_mul_f32_e32 v85, v81, v81
	v_max_f32_e32 v81, v86, v86
	v_mul_f32_e32 v86, v82, v82
	v_max_f32_e32 v84, 0, v84
	v_mul_f32_e32 v80, v80, v80
	v_max_f32_e32 v81, 0, v81
	v_max_f32_e32 v82, 0, v87
	v_max_f32_e32 v83, 0, v83
	v_mul_f32_e32 v84, v84, v84
	v_mul_f32_e32 v81, v81, v81
	v_mul_f32_e32 v82, v82, v82
	v_mul_f32_e32 v83, v83, v83
	v_cvt_pk_bf16_f32 v80, v84, v80
	v_cvt_pk_bf16_f32 v81, v81, v82
	v_cvt_pk_bf16_f32 v82, v88, v85
	v_cvt_pk_bf16_f32 v83, v86, v83
	global_store_dwordx4 v[96:97], v[80:83], off offset:256
	v_max_f32_e32 v72, 0, v72
	s_nop 0
	v_or_b32_e32 v80, 48, v152
	v_ashrrev_i32_e32 v81, 31, v80
	v_mul_f32_e32 v82, v72, v72
	v_max_f32_e32 v73, 0, v73
	v_max_f32_e32 v74, 0, v74
	v_lshlrev_b64 v[80:81], 13, v[80:81]
	v_max_f32_e32 v72, 0, v77
	v_mul_f32_e32 v77, v73, v73
	v_max_f32_e32 v73, v78, v78
	v_mul_f32_e32 v78, v74, v74
	v_lshl_add_u64 v[80:81], s[44:45], 0, v[80:81]
	v_max_f32_e32 v76, 0, v76
	v_mul_f32_e32 v72, v72, v72
	v_max_f32_e32 v73, 0, v73
	v_max_f32_e32 v74, 0, v79
	v_max_f32_e32 v75, 0, v75
	v_lshl_add_u64 v[80:81], v[80:81], 0, v[156:157]
	v_mul_f32_e32 v76, v76, v76
	v_mul_f32_e32 v73, v73, v73
	v_mul_f32_e32 v74, v74, v74
	v_mul_f32_e32 v75, v75, v75
	v_cvt_pk_bf16_f32 v72, v76, v72
	v_max_f32_e32 v64, 0, v64
	v_max_f32_e32 v65, 0, v65
	v_max_f32_e32 v66, 0, v66
	v_cvt_pk_bf16_f32 v73, v73, v74
	v_cvt_pk_bf16_f32 v74, v82, v77
	v_cvt_pk_bf16_f32 v75, v78, v75
	global_store_dwordx4 v[80:81], v[72:75], off
	s_nop 1
	v_mul_f32_e32 v72, v64, v64
	v_max_f32_e32 v64, v69, v69
	v_mul_f32_e32 v69, v65, v65
	v_max_f32_e32 v65, v70, v70
	v_mul_f32_e32 v70, v66, v66
	v_max_f32_e32 v64, 0, v64
	v_max_f32_e32 v65, 0, v65
	v_max_f32_e32 v66, 0, v71
	v_max_f32_e32 v68, 0, v68
	v_mul_f32_e32 v64, v64, v64
	v_mul_f32_e32 v65, v65, v65
	v_max_f32_e32 v67, 0, v67
	v_mul_f32_e32 v66, v66, v66
	v_mul_f32_e32 v68, v68, v68
	v_mul_f32_e32 v67, v67, v67
	v_cvt_pk_bf16_f32 v64, v68, v64
	v_cvt_pk_bf16_f32 v65, v65, v66
	v_cvt_pk_bf16_f32 v66, v72, v69
	v_max_f32_e32 v56, 0, v56
	v_cvt_pk_bf16_f32 v67, v70, v67
	global_store_dwordx4 v[80:81], v[64:67], off offset:256
	v_max_f32_e32 v57, 0, v57
	s_nop 0
	v_mul_f32_e32 v66, v56, v56
	v_max_f32_e32 v58, 0, v58
	v_max_f32_e32 v60, 0, v60
	v_max_f32_e32 v56, 0, v61
	v_mul_f32_e32 v61, v57, v57
	v_max_f32_e32 v57, v62, v62
	v_mul_f32_e32 v62, v58, v58
	v_mul_f32_e32 v60, v60, v60
	v_mul_f32_e32 v56, v56, v56
	v_max_f32_e32 v57, 0, v57
	v_max_f32_e32 v58, 0, v63
	v_mul_f32_e32 v57, v57, v57
	v_max_f32_e32 v59, 0, v59
	v_mul_f32_e32 v58, v58, v58
	v_cvt_pk_bf16_f32 v56, v60, v56
	v_add_co_u32_e32 v60, vcc, s67, v144
	v_mul_f32_e32 v59, v59, v59
	v_cvt_pk_bf16_f32 v57, v57, v58
	v_cvt_pk_bf16_f32 v58, v66, v61
	v_addc_co_u32_e32 v61, vcc, 0, v145, vcc
	v_max_f32_e32 v48, 0, v48
	v_max_f32_e32 v49, 0, v49
	v_max_f32_e32 v50, 0, v50
	v_cvt_pk_bf16_f32 v59, v62, v59
	global_store_dwordx4 v[60:61], v[56:59], off
	s_nop 1
	v_mul_f32_e32 v56, v48, v48
	v_max_f32_e32 v48, v53, v53
	v_mul_f32_e32 v53, v49, v49
	v_max_f32_e32 v49, v54, v54
	v_mul_f32_e32 v54, v50, v50
	v_max_f32_e32 v48, 0, v48
	v_max_f32_e32 v49, 0, v49
	v_max_f32_e32 v50, 0, v55
	v_max_f32_e32 v52, 0, v52
	v_mul_f32_e32 v48, v48, v48
	v_mul_f32_e32 v49, v49, v49
	v_max_f32_e32 v51, 0, v51
	v_mul_f32_e32 v50, v50, v50
	v_lshl_add_u64 v[64:65], v[144:145], 0, s[12:13]
	v_mul_f32_e32 v52, v52, v52
	v_mul_f32_e32 v51, v51, v51
	v_cvt_pk_bf16_f32 v48, v52, v48
	v_cvt_pk_bf16_f32 v49, v49, v50
	v_cvt_pk_bf16_f32 v50, v56, v53
	v_max_f32_e32 v40, 0, v40
	v_cvt_pk_bf16_f32 v51, v54, v51
	global_store_dwordx4 v[64:65], v[48:51], off offset:256
	v_max_f32_e32 v41, 0, v41
	s_nop 0
	v_mul_f32_e32 v50, v40, v40
	v_max_f32_e32 v42, 0, v42
	v_max_f32_e32 v44, 0, v44
	v_max_f32_e32 v40, 0, v45
	v_mul_f32_e32 v45, v41, v41
	v_max_f32_e32 v41, v46, v46
	v_mul_f32_e32 v46, v42, v42
	v_mul_f32_e32 v44, v44, v44
	v_mul_f32_e32 v40, v40, v40
	v_max_f32_e32 v41, 0, v41
	v_max_f32_e32 v42, 0, v47
	v_mul_f32_e32 v41, v41, v41
	v_max_f32_e32 v43, 0, v43
	v_mul_f32_e32 v42, v42, v42
	v_cvt_pk_bf16_f32 v40, v44, v40
	v_add_co_u32_e32 v44, vcc, s68, v144
	v_mul_f32_e32 v43, v43, v43
	v_cvt_pk_bf16_f32 v41, v41, v42
	v_cvt_pk_bf16_f32 v42, v50, v45
	v_addc_co_u32_e32 v45, vcc, 0, v145, vcc
	v_max_f32_e32 v32, 0, v32
	v_max_f32_e32 v33, 0, v33
	v_max_f32_e32 v34, 0, v34
	v_cvt_pk_bf16_f32 v43, v46, v43
	global_store_dwordx4 v[44:45], v[40:43], off
	s_nop 1
	v_mul_f32_e32 v40, v32, v32
	v_max_f32_e32 v32, v37, v37
	v_mul_f32_e32 v37, v33, v33
	v_max_f32_e32 v33, v38, v38
	v_mul_f32_e32 v38, v34, v34
	v_max_f32_e32 v32, 0, v32
	v_max_f32_e32 v33, 0, v33
	v_max_f32_e32 v34, 0, v39
	v_max_f32_e32 v36, 0, v36
	v_mul_f32_e32 v32, v32, v32
	v_mul_f32_e32 v33, v33, v33
	v_max_f32_e32 v35, 0, v35
	v_mul_f32_e32 v34, v34, v34
	v_lshl_add_u64 v[48:49], v[144:145], 0, s[14:15]
	v_mul_f32_e32 v36, v36, v36
	v_mul_f32_e32 v35, v35, v35
	v_cvt_pk_bf16_f32 v32, v36, v32
	v_cvt_pk_bf16_f32 v33, v33, v34
	v_cvt_pk_bf16_f32 v34, v40, v37
	v_max_f32_e32 v24, 0, v24
	v_cvt_pk_bf16_f32 v35, v38, v35
	global_store_dwordx4 v[48:49], v[32:35], off offset:256
	v_max_f32_e32 v25, 0, v25
	s_nop 0
	v_mul_f32_e32 v34, v24, v24
	v_max_f32_e32 v26, 0, v26
	v_max_f32_e32 v28, 0, v28
	v_max_f32_e32 v24, 0, v29
	v_mul_f32_e32 v29, v25, v25
	v_max_f32_e32 v25, v30, v30
	v_mul_f32_e32 v30, v26, v26
	v_mul_f32_e32 v28, v28, v28
	v_mul_f32_e32 v24, v24, v24
	v_max_f32_e32 v25, 0, v25
	v_max_f32_e32 v26, 0, v31
	v_mul_f32_e32 v25, v25, v25
	v_max_f32_e32 v27, 0, v27
	v_mul_f32_e32 v26, v26, v26
	v_cvt_pk_bf16_f32 v24, v28, v24
	v_add_co_u32_e32 v28, vcc, s69, v144
	v_mul_f32_e32 v27, v27, v27
	v_cvt_pk_bf16_f32 v25, v25, v26
	v_cvt_pk_bf16_f32 v26, v34, v29
	v_addc_co_u32_e32 v29, vcc, 0, v145, vcc
	v_max_f32_e32 v16, 0, v16
	v_max_f32_e32 v17, 0, v17
	v_max_f32_e32 v18, 0, v18
	v_cvt_pk_bf16_f32 v27, v30, v27
	global_store_dwordx4 v[28:29], v[24:27], off
	s_nop 1
	v_mul_f32_e32 v24, v16, v16
	v_max_f32_e32 v16, v21, v21
	v_mul_f32_e32 v21, v17, v17
	v_max_f32_e32 v17, v22, v22
	v_mul_f32_e32 v22, v18, v18
	v_max_f32_e32 v16, 0, v16
	v_max_f32_e32 v17, 0, v17
	v_max_f32_e32 v18, 0, v23
	v_max_f32_e32 v20, 0, v20
	v_mul_f32_e32 v16, v16, v16
	v_mul_f32_e32 v17, v17, v17
	v_max_f32_e32 v19, 0, v19
	v_mul_f32_e32 v18, v18, v18
	v_lshl_add_u64 v[32:33], v[144:145], 0, s[16:17]
	v_mul_f32_e32 v20, v20, v20
	v_mul_f32_e32 v19, v19, v19
	v_cvt_pk_bf16_f32 v16, v20, v16
	v_cvt_pk_bf16_f32 v17, v17, v18
	v_cvt_pk_bf16_f32 v18, v24, v21
	v_max_f32_e32 v8, 0, v8
	v_cvt_pk_bf16_f32 v19, v22, v19
	global_store_dwordx4 v[32:33], v[16:19], off offset:256
	v_max_f32_e32 v9, 0, v9
	s_nop 0
	v_mul_f32_e32 v18, v8, v8
	v_max_f32_e32 v10, 0, v10
	v_max_f32_e32 v12, 0, v12
	v_max_f32_e32 v8, 0, v13
	v_mul_f32_e32 v13, v9, v9
	v_max_f32_e32 v9, v14, v14
	v_mul_f32_e32 v14, v10, v10
	v_mul_f32_e32 v12, v12, v12
	v_mul_f32_e32 v8, v8, v8
	v_max_f32_e32 v9, 0, v9
	v_max_f32_e32 v10, 0, v15
	v_mul_f32_e32 v9, v9, v9
	v_max_f32_e32 v11, 0, v11
	v_mul_f32_e32 v10, v10, v10
	v_cvt_pk_bf16_f32 v8, v12, v8
	v_add_co_u32_e32 v12, vcc, s70, v144
	v_mul_f32_e32 v11, v11, v11
	v_cvt_pk_bf16_f32 v9, v9, v10
	v_cvt_pk_bf16_f32 v10, v18, v13
	v_addc_co_u32_e32 v13, vcc, 0, v145, vcc
	v_max_f32_e32 v0, 0, v0
	v_max_f32_e32 v1, 0, v1
	v_max_f32_e32 v2, 0, v2
	v_cvt_pk_bf16_f32 v11, v14, v11
	global_store_dwordx4 v[12:13], v[8:11], off
	s_nop 1
	v_mul_f32_e32 v8, v0, v0
	v_max_f32_e32 v0, v5, v5
	v_mul_f32_e32 v5, v1, v1
	v_max_f32_e32 v1, v6, v6
	v_mul_f32_e32 v6, v2, v2
	v_max_f32_e32 v0, 0, v0
	v_max_f32_e32 v1, 0, v1
	v_max_f32_e32 v2, 0, v7
	v_max_f32_e32 v3, 0, v3
	v_lshl_add_u64 v[16:17], v[144:145], 0, s[18:19]
	v_max_f32_e32 v4, 0, v4
	v_mul_f32_e32 v0, v0, v0
	v_mul_f32_e32 v1, v1, v1
	v_mul_f32_e32 v2, v2, v2
	v_mul_f32_e32 v3, v3, v3
	s_andn2_b64 vcc, exec, s[4:5]
	s_mov_b64 s[4:5], -1
	v_mul_f32_e32 v4, v4, v4
	v_cvt_pk_bf16_f32 v0, v4, v0
	v_cvt_pk_bf16_f32 v1, v1, v2
	v_cvt_pk_bf16_f32 v2, v8, v5
	v_cvt_pk_bf16_f32 v3, v6, v3
	global_store_dwordx4 v[16:17], v[0:3], off offset:256
	s_cbranch_vccnz .LBB0_1878
	s_andn2_b64 vcc, exec, s[6:7]
	s_cbranch_vccnz .LBB0_1877
	s_barrier
	s_branch .LBB0_1877
